# EpiBf16 epilogues: bias-zero pk_adds removed (cvt straight from accumulators), s_nop after stores
# baseline (speedup 1.0000x reference)
.LBB0_440:
	v_lshl_add_u32 v142, s17, 8, v131
	v_lshl_or_b32 v131, s18, 8, v158
	v_or_b32_e32 v140, s23, v131
	v_readlane_b32 s0, v252, 2
	v_ashrrev_i32_e32 v141, 31, v140
	v_readlane_b32 s1, v252, 3
	v_ashrrev_i32_e32 v143, 31, v142
	v_lshl_add_u64 v[144:145], v[140:141], 1, s[0:1]
	v_lshlrev_b64 v[140:141], 11, v[142:143]
	v_lshl_add_u64 v[140:141], v[144:145], 0, v[140:141]
	v_cvt_pk_bf16_f32 v125, v124, v125
	v_cvt_pk_bf16_f32 v124, v122, v123
	v_cvt_pk_bf16_f32 v122, v126, v127
	v_cvt_pk_bf16_f32 v123, v128, v129
	global_store_dwordx4 v[140:141], v[122:125], off
	s_nop 1
	v_pk_add_f32 v[114:115], v[114:115], 0 op_sel_hi:[1,0]
	v_cvt_pk_bf16_f32 v113, v112, v113
	v_cvt_pk_bf16_f32 v112, v110, v111
	v_cvt_pk_bf16_f32 v110, v118, v119
	v_cvt_pk_bf16_f32 v111, v120, v121
	global_store_dwordx4 v[140:141], v[110:113], off offset:256
	s_nop 1
	v_pk_add_f32 v[98:99], v[98:99], 0 op_sel_hi:[1,0]
	v_or_b32_e32 v110, 16, v142
	v_ashrrev_i32_e32 v111, 31, v110
	v_lshlrev_b64 v[110:111], 11, v[110:111]
	v_lshl_add_u64 v[110:111], v[144:145], 0, v[110:111]
	v_pk_add_f32 v[112:113], v[116:117], 0 op_sel_hi:[1,0]
	v_pk_add_f32 v[116:117], v[108:109], 0 op_sel_hi:[1,0]
	v_pk_add_f32 v[108:109], v[106:107], 0 op_sel_hi:[1,0]
	v_cvt_pk_bf16_f32 v106, v114, v115
	v_cvt_pk_bf16_f32 v107, v112, v113
	v_cvt_pk_bf16_f32 v108, v108, v109
	v_cvt_pk_bf16_f32 v109, v116, v117
	global_store_dwordx4 v[110:111], v[106:109], off
	s_nop 1
	v_pk_add_f32 v[82:83], v[82:83], 0 op_sel_hi:[1,0]
	v_cvt_pk_bf16_f32 v97, v96, v97
	v_cvt_pk_bf16_f32 v96, v94, v95
	v_cvt_pk_bf16_f32 v94, v102, v103
	v_cvt_pk_bf16_f32 v95, v104, v105
	global_store_dwordx4 v[110:111], v[94:97], off offset:256
	s_nop 1
	s_mov_b64 s[0:1], 0x40000
	v_or_b32_e32 v94, 32, v142
	v_ashrrev_i32_e32 v95, 31, v94
	v_lshlrev_b64 v[94:95], 11, v[94:95]
	v_lshl_add_u64 v[94:95], v[144:145], 0, v[94:95]
	v_pk_add_f32 v[96:97], v[100:101], 0 op_sel_hi:[1,0]
	v_pk_add_f32 v[100:101], v[92:93], 0 op_sel_hi:[1,0]
	v_pk_add_f32 v[92:93], v[90:91], 0 op_sel_hi:[1,0]
	v_cvt_pk_bf16_f32 v90, v98, v99
	v_cvt_pk_bf16_f32 v91, v96, v97
	v_cvt_pk_bf16_f32 v92, v92, v93
	v_cvt_pk_bf16_f32 v93, v100, v101
	global_store_dwordx4 v[94:95], v[90:93], off
	s_nop 1
	v_cvt_pk_bf16_f32 v81, v80, v81
	v_cvt_pk_bf16_f32 v80, v78, v79
	v_cvt_pk_bf16_f32 v78, v86, v87
	v_cvt_pk_bf16_f32 v79, v88, v89
	global_store_dwordx4 v[94:95], v[78:81], off offset:256
	s_nop 1
	v_pk_add_f32 v[50:51], v[50:51], 0 op_sel_hi:[1,0]
	v_or_b32_e32 v78, 48, v142
	v_ashrrev_i32_e32 v79, 31, v78
	v_lshlrev_b64 v[78:79], 11, v[78:79]
	v_lshl_add_u64 v[78:79], v[144:145], 0, v[78:79]
	v_pk_add_f32 v[80:81], v[84:85], 0 op_sel_hi:[1,0]
	v_pk_add_f32 v[84:85], v[76:77], 0 op_sel_hi:[1,0]
	v_pk_add_f32 v[76:77], v[74:75], 0 op_sel_hi:[1,0]
	v_cvt_pk_bf16_f32 v74, v82, v83
	v_cvt_pk_bf16_f32 v75, v80, v81
	v_cvt_pk_bf16_f32 v76, v76, v77
	v_cvt_pk_bf16_f32 v77, v84, v85
	global_store_dwordx4 v[78:79], v[74:77], off
	s_nop 1
	v_pk_add_f32 v[34:35], v[34:35], 0 op_sel_hi:[1,0]
	v_cvt_pk_bf16_f32 v69, v68, v69
	v_cvt_pk_bf16_f32 v68, v66, v67
	v_cvt_pk_bf16_f32 v66, v70, v71
	v_cvt_pk_bf16_f32 v67, v72, v73
	global_store_dwordx4 v[78:79], v[66:69], off offset:256
	s_nop 1
	v_pk_add_f32 v[18:19], v[18:19], 0 op_sel_hi:[1,0]
	v_lshl_add_u64 v[66:67], v[140:141], 0, s[0:1]
	s_mov_b32 s0, 0x40000
	v_cvt_pk_bf16_f32 v61, v60, v61
	v_cvt_pk_bf16_f32 v60, v58, v59
	v_cvt_pk_bf16_f32 v58, v62, v63
	v_add_co_u32_e32 v62, vcc, s0, v140
	v_cvt_pk_bf16_f32 v59, v64, v65
	s_mov_b64 s[0:1], 0x48000
	s_nop 0
	v_addc_co_u32_e32 v63, vcc, 0, v141, vcc
	global_store_dwordx4 v[62:63], v[58:61], off
	s_nop 1
	s_mov_b32 s28, s33
	v_cvt_pk_bf16_f32 v49, v48, v49
	v_cvt_pk_bf16_f32 v48, v46, v47
	v_cvt_pk_bf16_f32 v46, v54, v55
	v_cvt_pk_bf16_f32 v47, v56, v57
	v_readlane_b32 s30, v253, 58
	global_store_dwordx4 v[66:67], v[46:49], off offset:256
	s_nop 1
	s_nop 1
	v_lshl_add_u64 v[46:47], v[140:141], 0, s[0:1]
	v_pk_add_f32 v[48:49], v[52:53], 0 op_sel_hi:[1,0]
	s_mov_b32 s0, 0x48000
	v_pk_add_f32 v[52:53], v[44:45], 0 op_sel_hi:[1,0]
	v_pk_add_f32 v[44:45], v[42:43], 0 op_sel_hi:[1,0]
	v_cvt_pk_bf16_f32 v42, v50, v51
	v_cvt_pk_bf16_f32 v43, v48, v49
	v_add_co_u32_e32 v48, vcc, s0, v140
	v_cvt_pk_bf16_f32 v44, v44, v45
	v_cvt_pk_bf16_f32 v45, v52, v53
	s_mov_b64 s[0:1], 0x50000
	s_nop 0
	v_addc_co_u32_e32 v49, vcc, 0, v141, vcc
	global_store_dwordx4 v[48:49], v[42:45], off
	s_nop 1
	s_nop 1
	v_cvt_pk_bf16_f32 v33, v32, v33
	v_cvt_pk_bf16_f32 v32, v30, v31
	v_cvt_pk_bf16_f32 v30, v38, v39
	v_cvt_pk_bf16_f32 v31, v40, v41
	s_nop 0
	global_store_dwordx4 v[46:47], v[30:33], off offset:256
	s_nop 1
	s_nop 1
	v_lshl_add_u64 v[30:31], v[140:141], 0, s[0:1]
	v_pk_add_f32 v[32:33], v[36:37], 0 op_sel_hi:[1,0]
	s_mov_b32 s0, 0x50000
	v_pk_add_f32 v[36:37], v[28:29], 0 op_sel_hi:[1,0]
	v_pk_add_f32 v[28:29], v[26:27], 0 op_sel_hi:[1,0]
	v_cvt_pk_bf16_f32 v26, v34, v35
	v_cvt_pk_bf16_f32 v27, v32, v33
	v_add_co_u32_e32 v32, vcc, s0, v140
	v_cvt_pk_bf16_f32 v28, v28, v29
	v_cvt_pk_bf16_f32 v29, v36, v37
	s_mov_b64 s[0:1], 0x58000
	s_nop 0
	v_addc_co_u32_e32 v33, vcc, 0, v141, vcc
	global_store_dwordx4 v[32:33], v[26:29], off
	s_nop 1
	s_nop 1
	v_cvt_pk_bf16_f32 v17, v16, v17
	v_cvt_pk_bf16_f32 v16, v14, v15
	v_cvt_pk_bf16_f32 v14, v22, v23
	v_cvt_pk_bf16_f32 v15, v24, v25
	s_nop 0
	global_store_dwordx4 v[30:31], v[14:17], off offset:256
	s_nop 1
	s_nop 1
	v_lshl_add_u64 v[14:15], v[140:141], 0, s[0:1]
	v_pk_add_f32 v[16:17], v[20:21], 0 op_sel_hi:[1,0]
	s_mov_b32 s0, 0x58000
	v_pk_add_f32 v[20:21], v[12:13], 0 op_sel_hi:[1,0]
	v_pk_add_f32 v[12:13], v[10:11], 0 op_sel_hi:[1,0]
	v_cvt_pk_bf16_f32 v10, v18, v19
	v_cvt_pk_bf16_f32 v11, v16, v17
	v_add_co_u32_e32 v16, vcc, s0, v140
	v_cvt_pk_bf16_f32 v12, v12, v13
	v_cvt_pk_bf16_f32 v13, v20, v21
	s_nop 1
	v_addc_co_u32_e32 v17, vcc, 0, v141, vcc
	global_store_dwordx4 v[16:17], v[10:13], off
	s_nop 1
	s_nop 1
	v_cvt_pk_bf16_f32 v5, v4, v5
	v_cvt_pk_bf16_f32 v4, v2, v3
	v_cvt_pk_bf16_f32 v2, v6, v7
	v_cvt_pk_bf16_f32 v3, v8, v9
	s_nop 0
	global_store_dwordx4 v[14:15], v[2:5], off offset:256
	s_nop 1
	s_waitcnt vmcnt(0)
	s_barrier

.LBB0_498:
	v_lshl_add_u32 v152, s43, 8, v146
	v_lshl_or_b32 v144, s42, 8, v148
	v_readlane_b32 s2, v252, 2
	v_ashrrev_i32_e32 v145, 31, v144
	v_readlane_b32 s3, v252, 3
	v_ashrrev_i32_e32 v153, 31, v152
	v_lshl_add_u64 v[154:155], v[144:145], 1, s[2:3]
	v_lshlrev_b64 v[144:145], 11, v[152:153]
	v_lshl_add_u64 v[144:145], v[154:155], 0, v[144:145]
	v_cvt_pk_bf16_f32 v125, v124, v125
	v_cvt_pk_bf16_f32 v124, v122, v123
	v_cvt_pk_bf16_f32 v122, v126, v127
	v_cvt_pk_bf16_f32 v123, v128, v129
	global_store_dwordx4 v[144:145], v[122:125], off
	s_nop 1
	v_pk_add_f32 v[114:115], v[114:115], 0 op_sel_hi:[1,0]
	v_cvt_pk_bf16_f32 v113, v112, v113
	v_cvt_pk_bf16_f32 v112, v110, v111
	v_cvt_pk_bf16_f32 v110, v118, v119
	v_cvt_pk_bf16_f32 v111, v120, v121
	global_store_dwordx4 v[144:145], v[110:113], off offset:256
	s_nop 1
	v_pk_add_f32 v[98:99], v[98:99], 0 op_sel_hi:[1,0]
	v_or_b32_e32 v110, 16, v152
	v_ashrrev_i32_e32 v111, 31, v110
	v_lshlrev_b64 v[110:111], 11, v[110:111]
	v_lshl_add_u64 v[110:111], v[154:155], 0, v[110:111]
	v_pk_add_f32 v[112:113], v[116:117], 0 op_sel_hi:[1,0]
	v_pk_add_f32 v[116:117], v[108:109], 0 op_sel_hi:[1,0]
	v_pk_add_f32 v[108:109], v[106:107], 0 op_sel_hi:[1,0]
	v_cvt_pk_bf16_f32 v106, v114, v115
	v_cvt_pk_bf16_f32 v107, v112, v113
	v_cvt_pk_bf16_f32 v108, v108, v109
	v_cvt_pk_bf16_f32 v109, v116, v117
	global_store_dwordx4 v[110:111], v[106:109], off
	s_nop 1
	v_pk_add_f32 v[82:83], v[82:83], 0 op_sel_hi:[1,0]
	v_cvt_pk_bf16_f32 v97, v96, v97
	v_cvt_pk_bf16_f32 v96, v94, v95
	v_cvt_pk_bf16_f32 v94, v102, v103
	v_cvt_pk_bf16_f32 v95, v104, v105
	global_store_dwordx4 v[110:111], v[94:97], off offset:256
	s_nop 1
	s_mov_b64 s[2:3], 0x40000
	v_or_b32_e32 v94, 32, v152
	v_ashrrev_i32_e32 v95, 31, v94
	v_lshlrev_b64 v[94:95], 11, v[94:95]
	v_lshl_add_u64 v[94:95], v[154:155], 0, v[94:95]
	v_pk_add_f32 v[96:97], v[100:101], 0 op_sel_hi:[1,0]
	v_pk_add_f32 v[100:101], v[92:93], 0 op_sel_hi:[1,0]
	v_pk_add_f32 v[92:93], v[90:91], 0 op_sel_hi:[1,0]
	v_cvt_pk_bf16_f32 v90, v98, v99
	v_cvt_pk_bf16_f32 v91, v96, v97
	v_cvt_pk_bf16_f32 v92, v92, v93
	v_cvt_pk_bf16_f32 v93, v100, v101
	global_store_dwordx4 v[94:95], v[90:93], off
	s_nop 1
	v_cvt_pk_bf16_f32 v81, v80, v81
	v_cvt_pk_bf16_f32 v80, v78, v79
	v_cvt_pk_bf16_f32 v78, v86, v87
	v_cvt_pk_bf16_f32 v79, v88, v89
	global_store_dwordx4 v[94:95], v[78:81], off offset:256
	s_nop 1
	v_pk_add_f32 v[50:51], v[50:51], 0 op_sel_hi:[1,0]
	v_or_b32_e32 v78, 48, v152
	v_ashrrev_i32_e32 v79, 31, v78
	v_lshlrev_b64 v[78:79], 11, v[78:79]
	v_lshl_add_u64 v[78:79], v[154:155], 0, v[78:79]
	v_pk_add_f32 v[80:81], v[84:85], 0 op_sel_hi:[1,0]
	v_pk_add_f32 v[84:85], v[76:77], 0 op_sel_hi:[1,0]
	v_pk_add_f32 v[76:77], v[74:75], 0 op_sel_hi:[1,0]
	v_cvt_pk_bf16_f32 v74, v82, v83
	v_cvt_pk_bf16_f32 v75, v80, v81
	v_cvt_pk_bf16_f32 v76, v76, v77
	v_cvt_pk_bf16_f32 v77, v84, v85
	global_store_dwordx4 v[78:79], v[74:77], off
	s_nop 1
	v_pk_add_f32 v[34:35], v[34:35], 0 op_sel_hi:[1,0]
	v_cvt_pk_bf16_f32 v69, v68, v69
	v_cvt_pk_bf16_f32 v68, v66, v67
	v_cvt_pk_bf16_f32 v66, v70, v71
	v_cvt_pk_bf16_f32 v67, v72, v73
	global_store_dwordx4 v[78:79], v[66:69], off offset:256
	s_nop 1
	v_pk_add_f32 v[18:19], v[18:19], 0 op_sel_hi:[1,0]
	v_lshl_add_u64 v[66:67], v[144:145], 0, s[2:3]
	s_mov_b32 s2, 0x40000
	v_cvt_pk_bf16_f32 v61, v60, v61
	v_cvt_pk_bf16_f32 v60, v58, v59
	v_cvt_pk_bf16_f32 v58, v62, v63
	v_add_co_u32_e32 v62, vcc, s2, v144
	v_cvt_pk_bf16_f32 v59, v64, v65
	s_mov_b64 s[2:3], 0x48000
	s_nop 0
	v_addc_co_u32_e32 v63, vcc, 0, v145, vcc
	global_store_dwordx4 v[62:63], v[58:61], off
	s_nop 1
	s_nop 0
	v_cvt_pk_bf16_f32 v49, v48, v49
	v_cvt_pk_bf16_f32 v48, v46, v47
	v_cvt_pk_bf16_f32 v46, v54, v55
	v_cvt_pk_bf16_f32 v47, v56, v57
	s_nop 0
	global_store_dwordx4 v[66:67], v[46:49], off offset:256
	s_nop 1
	s_nop 1
	v_lshl_add_u64 v[46:47], v[144:145], 0, s[2:3]
	v_pk_add_f32 v[48:49], v[52:53], 0 op_sel_hi:[1,0]
	s_mov_b32 s2, 0x48000
	v_pk_add_f32 v[52:53], v[44:45], 0 op_sel_hi:[1,0]
	v_pk_add_f32 v[44:45], v[42:43], 0 op_sel_hi:[1,0]
	v_cvt_pk_bf16_f32 v42, v50, v51
	v_cvt_pk_bf16_f32 v43, v48, v49
	v_add_co_u32_e32 v48, vcc, s2, v144
	v_cvt_pk_bf16_f32 v44, v44, v45
	v_cvt_pk_bf16_f32 v45, v52, v53
	s_mov_b64 s[2:3], 0x50000
	s_nop 0
	v_addc_co_u32_e32 v49, vcc, 0, v145, vcc
	global_store_dwordx4 v[48:49], v[42:45], off
	s_nop 1
	s_nop 1
	v_cvt_pk_bf16_f32 v33, v32, v33
	v_cvt_pk_bf16_f32 v32, v30, v31
	v_cvt_pk_bf16_f32 v30, v38, v39
	v_cvt_pk_bf16_f32 v31, v40, v41
	s_nop 0
	global_store_dwordx4 v[46:47], v[30:33], off offset:256
	s_nop 1
	s_nop 1
	v_lshl_add_u64 v[30:31], v[144:145], 0, s[2:3]
	v_pk_add_f32 v[32:33], v[36:37], 0 op_sel_hi:[1,0]
	s_mov_b32 s2, 0x50000
	v_pk_add_f32 v[36:37], v[28:29], 0 op_sel_hi:[1,0]
	v_pk_add_f32 v[28:29], v[26:27], 0 op_sel_hi:[1,0]
	v_cvt_pk_bf16_f32 v26, v34, v35
	v_cvt_pk_bf16_f32 v27, v32, v33
	v_add_co_u32_e32 v32, vcc, s2, v144
	v_cvt_pk_bf16_f32 v28, v28, v29
	v_cvt_pk_bf16_f32 v29, v36, v37
	s_mov_b64 s[2:3], 0x58000
	s_nop 0
	v_addc_co_u32_e32 v33, vcc, 0, v145, vcc
	global_store_dwordx4 v[32:33], v[26:29], off
	s_nop 1
	s_nop 1
	v_cvt_pk_bf16_f32 v17, v16, v17
	v_cvt_pk_bf16_f32 v16, v14, v15
	v_cvt_pk_bf16_f32 v14, v22, v23
	v_cvt_pk_bf16_f32 v15, v24, v25
	s_nop 0
	global_store_dwordx4 v[30:31], v[14:17], off offset:256
	s_nop 1
	s_nop 1
	v_lshl_add_u64 v[14:15], v[144:145], 0, s[2:3]
	v_pk_add_f32 v[16:17], v[20:21], 0 op_sel_hi:[1,0]
	s_mov_b32 s2, 0x58000
	v_pk_add_f32 v[20:21], v[12:13], 0 op_sel_hi:[1,0]
	v_pk_add_f32 v[12:13], v[10:11], 0 op_sel_hi:[1,0]
	v_cvt_pk_bf16_f32 v10, v18, v19
	v_cvt_pk_bf16_f32 v11, v16, v17
	v_add_co_u32_e32 v16, vcc, s2, v144
	v_cvt_pk_bf16_f32 v12, v12, v13
	v_cvt_pk_bf16_f32 v13, v20, v21
	s_mov_b64 s[2:3], -1
	s_nop 0
	v_addc_co_u32_e32 v17, vcc, 0, v145, vcc
	global_store_dwordx4 v[16:17], v[10:13], off
	s_nop 1
	s_andn2_b64 vcc, exec, s[12:13]
	s_nop 0
	v_cvt_pk_bf16_f32 v5, v4, v5
	v_cvt_pk_bf16_f32 v4, v2, v3
	v_cvt_pk_bf16_f32 v2, v6, v7
	v_cvt_pk_bf16_f32 v3, v8, v9
	s_nop 0
	global_store_dwordx4 v[14:15], v[2:5], off offset:256
	s_nop 1
	s_cbranch_vccnz .LBB0_486
	s_andn2_b64 vcc, exec, s[4:5]
	s_cbranch_vccnz .LBB0_485
	s_barrier
	s_branch .LBB0_485

.LBB0_558:
	v_lshl_or_b32 v144, s47, 8, v150
	v_ashrrev_i32_e32 v145, 31, v144
	v_lshl_add_u32 v158, s24, 8, v148
	v_lshl_add_u64 v[144:145], v[144:145], 1, s[62:63]
	v_mad_i64_i32 v[154:155], s[2:3], v158, s46, v[144:145]
	v_cvt_pk_bf16_f32 v125, v124, v125
	v_cvt_pk_bf16_f32 v124, v122, v123
	v_cvt_pk_bf16_f32 v122, v126, v127
	v_cvt_pk_bf16_f32 v123, v128, v129
	global_store_dwordx4 v[154:155], v[122:125], off
	s_nop 1
	v_pk_add_f32 v[114:115], v[114:115], 0 op_sel_hi:[1,0]
	v_cvt_pk_bf16_f32 v113, v112, v113
	v_cvt_pk_bf16_f32 v112, v110, v111
	v_cvt_pk_bf16_f32 v110, v118, v119
	v_cvt_pk_bf16_f32 v111, v120, v121
	global_store_dwordx4 v[154:155], v[110:113], off offset:256
	s_nop 1
	v_pk_add_f32 v[98:99], v[98:99], 0 op_sel_hi:[1,0]
	v_or_b32_e32 v110, 16, v158
	v_mad_i64_i32 v[110:111], s[2:3], v110, s46, v[144:145]
	v_pk_add_f32 v[112:113], v[116:117], 0 op_sel_hi:[1,0]
	v_pk_add_f32 v[116:117], v[108:109], 0 op_sel_hi:[1,0]
	v_pk_add_f32 v[108:109], v[106:107], 0 op_sel_hi:[1,0]
	v_cvt_pk_bf16_f32 v106, v114, v115
	v_cvt_pk_bf16_f32 v107, v112, v113
	v_cvt_pk_bf16_f32 v108, v108, v109
	v_cvt_pk_bf16_f32 v109, v116, v117
	global_store_dwordx4 v[110:111], v[106:109], off
	s_nop 1
	v_pk_add_f32 v[82:83], v[82:83], 0 op_sel_hi:[1,0]
	v_cvt_pk_bf16_f32 v97, v96, v97
	v_cvt_pk_bf16_f32 v96, v94, v95
	v_cvt_pk_bf16_f32 v94, v102, v103
	v_cvt_pk_bf16_f32 v95, v104, v105
	global_store_dwordx4 v[110:111], v[94:97], off offset:256
	s_nop 1
	v_or_b32_e32 v94, 32, v158
	v_mad_i64_i32 v[94:95], s[2:3], v94, s46, v[144:145]
	v_pk_add_f32 v[96:97], v[100:101], 0 op_sel_hi:[1,0]
	v_pk_add_f32 v[100:101], v[92:93], 0 op_sel_hi:[1,0]
	v_pk_add_f32 v[92:93], v[90:91], 0 op_sel_hi:[1,0]
	v_cvt_pk_bf16_f32 v90, v98, v99
	v_cvt_pk_bf16_f32 v91, v96, v97
	v_cvt_pk_bf16_f32 v92, v92, v93
	v_cvt_pk_bf16_f32 v93, v100, v101
	global_store_dwordx4 v[94:95], v[90:93], off
	s_nop 1
	v_cvt_pk_bf16_f32 v81, v80, v81
	v_cvt_pk_bf16_f32 v80, v78, v79
	v_cvt_pk_bf16_f32 v78, v86, v87
	v_cvt_pk_bf16_f32 v79, v88, v89
	v_pk_add_f32 v[50:51], v[50:51], 0 op_sel_hi:[1,0]
	global_store_dwordx4 v[94:95], v[78:81], off offset:256
	s_nop 1
	v_or_b32_e32 v78, 48, v158
	v_mad_i64_i32 v[78:79], s[2:3], v78, s46, v[144:145]
	v_pk_add_f32 v[80:81], v[84:85], 0 op_sel_hi:[1,0]
	v_pk_add_f32 v[84:85], v[76:77], 0 op_sel_hi:[1,0]
	v_pk_add_f32 v[76:77], v[74:75], 0 op_sel_hi:[1,0]
	v_cvt_pk_bf16_f32 v74, v82, v83
	v_cvt_pk_bf16_f32 v75, v80, v81
	v_pk_add_f32 v[34:35], v[34:35], 0 op_sel_hi:[1,0]
	v_cvt_pk_bf16_f32 v76, v76, v77
	v_cvt_pk_bf16_f32 v77, v84, v85
	global_store_dwordx4 v[78:79], v[74:77], off
	s_nop 1
	v_cvt_pk_bf16_f32 v69, v68, v69
	v_cvt_pk_bf16_f32 v68, v66, v67
	v_cvt_pk_bf16_f32 v66, v70, v71
	v_cvt_pk_bf16_f32 v67, v72, v73
	v_pk_add_f32 v[18:19], v[18:19], 0 op_sel_hi:[1,0]
	global_store_dwordx4 v[78:79], v[66:69], off offset:256
	s_nop 1
	s_andn2_b64 vcc, exec, s[18:19]
	v_add_u32_e32 v66, 0x80, v158
	v_mad_i64_i32 v[66:67], s[2:3], v66, s46, v[144:145]
	v_cvt_pk_bf16_f32 v61, v60, v61
	v_cvt_pk_bf16_f32 v60, v58, v59
	v_cvt_pk_bf16_f32 v58, v62, v63
	v_cvt_pk_bf16_f32 v59, v64, v65
	global_store_dwordx4 v[66:67], v[58:61], off
	s_nop 1
	s_nop 1
	v_cvt_pk_bf16_f32 v49, v48, v49
	v_cvt_pk_bf16_f32 v48, v46, v47
	v_cvt_pk_bf16_f32 v46, v54, v55
	v_cvt_pk_bf16_f32 v47, v56, v57
	s_nop 0
	global_store_dwordx4 v[66:67], v[46:49], off offset:256
	s_nop 1
	s_nop 1
	v_add_u32_e32 v46, 0x90, v158
	v_mad_i64_i32 v[46:47], s[2:3], v46, s46, v[144:145]
	v_pk_add_f32 v[48:49], v[52:53], 0 op_sel_hi:[1,0]
	v_pk_add_f32 v[52:53], v[44:45], 0 op_sel_hi:[1,0]
	v_pk_add_f32 v[44:45], v[42:43], 0 op_sel_hi:[1,0]
	v_cvt_pk_bf16_f32 v42, v50, v51
	v_cvt_pk_bf16_f32 v43, v48, v49
	s_nop 0
	v_cvt_pk_bf16_f32 v44, v44, v45
	v_cvt_pk_bf16_f32 v45, v52, v53
	global_store_dwordx4 v[46:47], v[42:45], off
	s_nop 1
	s_nop 1
	v_cvt_pk_bf16_f32 v33, v32, v33
	v_cvt_pk_bf16_f32 v32, v30, v31
	v_cvt_pk_bf16_f32 v30, v38, v39
	v_cvt_pk_bf16_f32 v31, v40, v41
	s_nop 0
	global_store_dwordx4 v[46:47], v[30:33], off offset:256
	s_nop 1
	s_nop 1
	v_add_u32_e32 v30, 0xa0, v158
	v_mad_i64_i32 v[30:31], s[2:3], v30, s46, v[144:145]
	v_pk_add_f32 v[32:33], v[36:37], 0 op_sel_hi:[1,0]
	v_pk_add_f32 v[36:37], v[28:29], 0 op_sel_hi:[1,0]
	v_pk_add_f32 v[28:29], v[26:27], 0 op_sel_hi:[1,0]
	v_cvt_pk_bf16_f32 v26, v34, v35
	v_cvt_pk_bf16_f32 v27, v32, v33
	s_nop 0
	v_cvt_pk_bf16_f32 v28, v28, v29
	v_cvt_pk_bf16_f32 v29, v36, v37
	global_store_dwordx4 v[30:31], v[26:29], off
	s_nop 1
	s_nop 1
	v_cvt_pk_bf16_f32 v17, v16, v17
	v_cvt_pk_bf16_f32 v16, v14, v15
	v_cvt_pk_bf16_f32 v14, v22, v23
	v_cvt_pk_bf16_f32 v15, v24, v25
	s_nop 0
	global_store_dwordx4 v[30:31], v[14:17], off offset:256
	s_nop 1
	s_nop 1
	v_add_u32_e32 v14, 0xb0, v158
	v_mad_i64_i32 v[14:15], s[2:3], v14, s46, v[144:145]
	v_pk_add_f32 v[16:17], v[20:21], 0 op_sel_hi:[1,0]
	v_pk_add_f32 v[20:21], v[12:13], 0 op_sel_hi:[1,0]
	v_pk_add_f32 v[12:13], v[10:11], 0 op_sel_hi:[1,0]
	v_cvt_pk_bf16_f32 v10, v18, v19
	v_cvt_pk_bf16_f32 v11, v16, v17
	s_mov_b64 s[2:3], -1
	v_cvt_pk_bf16_f32 v12, v12, v13
	v_cvt_pk_bf16_f32 v13, v20, v21
	global_store_dwordx4 v[14:15], v[10:13], off
	s_nop 1
	s_nop 1
	v_cvt_pk_bf16_f32 v5, v4, v5
	v_cvt_pk_bf16_f32 v4, v2, v3
	v_cvt_pk_bf16_f32 v2, v6, v7
	v_cvt_pk_bf16_f32 v3, v8, v9
	s_nop 0
	global_store_dwordx4 v[14:15], v[2:5], off offset:256
	s_nop 1
	s_cbranch_vccnz .LBB0_550
	s_andn2_b64 vcc, exec, s[0:1]
	s_cbranch_vccnz .LBB0_549
	s_barrier
	s_branch .LBB0_549

.LBB0_649:
	v_lshl_or_b32 v130, s17, 8, v144
	v_or_b32_e32 v130, s21, v130
	v_lshl_add_u32 v132, s0, 8, v145
	v_lshlrev_b32_e32 v130, 1, v130
	v_mov_b32_e32 v131, 0
	v_lshl_add_u64 v[130:131], s[78:79], 0, v[130:131]
	s_mov_b64 s[0:1], 0x3800000
	v_ashrrev_i32_e32 v133, 31, v132
	v_lshl_add_u64 v[134:135], v[130:131], 0, s[0:1]
	v_lshlrev_b64 v[130:131], 12, v[132:133]
	v_lshl_add_u64 v[130:131], v[134:135], 0, v[130:131]
	v_cvt_pk_bf16_f32 v125, v124, v125
	v_cvt_pk_bf16_f32 v124, v122, v123
	v_cvt_pk_bf16_f32 v122, v126, v127
	v_cvt_pk_bf16_f32 v123, v128, v129
	global_store_dwordx4 v[130:131], v[122:125], off
	s_nop 1
	v_pk_add_f32 v[114:115], v[114:115], 0 op_sel_hi:[1,0]
	v_cvt_pk_bf16_f32 v113, v112, v113
	v_cvt_pk_bf16_f32 v112, v110, v111
	v_cvt_pk_bf16_f32 v110, v118, v119
	v_cvt_pk_bf16_f32 v111, v120, v121
	global_store_dwordx4 v[130:131], v[110:113], off offset:256
	s_nop 1
	v_pk_add_f32 v[98:99], v[98:99], 0 op_sel_hi:[1,0]
	v_or_b32_e32 v110, 16, v132
	v_ashrrev_i32_e32 v111, 31, v110
	v_lshlrev_b64 v[110:111], 12, v[110:111]
	v_lshl_add_u64 v[110:111], v[134:135], 0, v[110:111]
	v_pk_add_f32 v[112:113], v[116:117], 0 op_sel_hi:[1,0]
	v_pk_add_f32 v[116:117], v[108:109], 0 op_sel_hi:[1,0]
	v_pk_add_f32 v[108:109], v[106:107], 0 op_sel_hi:[1,0]
	v_cvt_pk_bf16_f32 v106, v114, v115
	v_cvt_pk_bf16_f32 v107, v112, v113
	v_cvt_pk_bf16_f32 v108, v108, v109
	v_cvt_pk_bf16_f32 v109, v116, v117
	global_store_dwordx4 v[110:111], v[106:109], off
	s_nop 1
	v_pk_add_f32 v[82:83], v[82:83], 0 op_sel_hi:[1,0]
	v_cvt_pk_bf16_f32 v97, v96, v97
	v_cvt_pk_bf16_f32 v96, v94, v95
	v_cvt_pk_bf16_f32 v94, v102, v103
	v_cvt_pk_bf16_f32 v95, v104, v105
	global_store_dwordx4 v[110:111], v[94:97], off offset:256
	s_nop 1
	s_mov_b64 s[0:1], 0x80000
	v_or_b32_e32 v94, 32, v132
	v_ashrrev_i32_e32 v95, 31, v94
	v_lshlrev_b64 v[94:95], 12, v[94:95]
	v_lshl_add_u64 v[94:95], v[134:135], 0, v[94:95]
	v_pk_add_f32 v[96:97], v[100:101], 0 op_sel_hi:[1,0]
	v_pk_add_f32 v[100:101], v[92:93], 0 op_sel_hi:[1,0]
	v_pk_add_f32 v[92:93], v[90:91], 0 op_sel_hi:[1,0]
	v_cvt_pk_bf16_f32 v90, v98, v99
	v_cvt_pk_bf16_f32 v91, v96, v97
	v_cvt_pk_bf16_f32 v92, v92, v93
	v_cvt_pk_bf16_f32 v93, v100, v101
	global_store_dwordx4 v[94:95], v[90:93], off
	s_nop 1
	v_cvt_pk_bf16_f32 v81, v80, v81
	v_cvt_pk_bf16_f32 v80, v78, v79
	v_cvt_pk_bf16_f32 v78, v86, v87
	v_cvt_pk_bf16_f32 v79, v88, v89
	global_store_dwordx4 v[94:95], v[78:81], off offset:256
	s_nop 1
	v_pk_add_f32 v[50:51], v[50:51], 0 op_sel_hi:[1,0]
	v_or_b32_e32 v78, 48, v132
	v_ashrrev_i32_e32 v79, 31, v78
	v_lshlrev_b64 v[78:79], 12, v[78:79]
	v_lshl_add_u64 v[78:79], v[134:135], 0, v[78:79]
	v_pk_add_f32 v[80:81], v[84:85], 0 op_sel_hi:[1,0]
	v_pk_add_f32 v[84:85], v[76:77], 0 op_sel_hi:[1,0]
	v_pk_add_f32 v[76:77], v[74:75], 0 op_sel_hi:[1,0]
	v_cvt_pk_bf16_f32 v74, v82, v83
	v_cvt_pk_bf16_f32 v75, v80, v81
	v_cvt_pk_bf16_f32 v76, v76, v77
	v_cvt_pk_bf16_f32 v77, v84, v85
	global_store_dwordx4 v[78:79], v[74:77], off
	s_nop 1
	v_pk_add_f32 v[34:35], v[34:35], 0 op_sel_hi:[1,0]
	v_cvt_pk_bf16_f32 v69, v68, v69
	v_cvt_pk_bf16_f32 v68, v66, v67
	v_cvt_pk_bf16_f32 v66, v70, v71
	v_cvt_pk_bf16_f32 v67, v72, v73
	global_store_dwordx4 v[78:79], v[66:69], off offset:256
	s_nop 1
	v_pk_add_f32 v[18:19], v[18:19], 0 op_sel_hi:[1,0]
	v_lshl_add_u64 v[66:67], v[130:131], 0, s[0:1]
	s_mov_b32 s0, 0x80000
	v_cvt_pk_bf16_f32 v61, v60, v61
	v_cvt_pk_bf16_f32 v60, v58, v59
	v_cvt_pk_bf16_f32 v58, v62, v63
	v_add_co_u32_e32 v62, vcc, s0, v130
	v_cvt_pk_bf16_f32 v59, v64, v65
	s_mov_b64 s[0:1], 0x90000
	s_nop 0
	v_addc_co_u32_e32 v63, vcc, 0, v131, vcc
	global_store_dwordx4 v[62:63], v[58:61], off
	s_nop 1
	s_nop 0
	v_cvt_pk_bf16_f32 v49, v48, v49
	v_cvt_pk_bf16_f32 v48, v46, v47
	v_cvt_pk_bf16_f32 v46, v54, v55
	v_cvt_pk_bf16_f32 v47, v56, v57
	s_nop 0
	global_store_dwordx4 v[66:67], v[46:49], off offset:256
	s_nop 1
	s_nop 1
	v_lshl_add_u64 v[46:47], v[130:131], 0, s[0:1]
	v_pk_add_f32 v[48:49], v[52:53], 0 op_sel_hi:[1,0]
	s_mov_b32 s0, 0x90000
	v_pk_add_f32 v[52:53], v[44:45], 0 op_sel_hi:[1,0]
	v_pk_add_f32 v[44:45], v[42:43], 0 op_sel_hi:[1,0]
	v_cvt_pk_bf16_f32 v42, v50, v51
	v_cvt_pk_bf16_f32 v43, v48, v49
	v_add_co_u32_e32 v48, vcc, s0, v130
	v_cvt_pk_bf16_f32 v44, v44, v45
	v_cvt_pk_bf16_f32 v45, v52, v53
	s_mov_b64 s[0:1], 0xa0000
	s_nop 0
	v_addc_co_u32_e32 v49, vcc, 0, v131, vcc
	global_store_dwordx4 v[48:49], v[42:45], off
	s_nop 1
	s_nop 1
	v_cvt_pk_bf16_f32 v33, v32, v33
	v_cvt_pk_bf16_f32 v32, v30, v31
	v_cvt_pk_bf16_f32 v30, v38, v39
	v_cvt_pk_bf16_f32 v31, v40, v41
	s_nop 0
	global_store_dwordx4 v[46:47], v[30:33], off offset:256
	s_nop 1
	s_nop 1
	v_lshl_add_u64 v[30:31], v[130:131], 0, s[0:1]
	v_pk_add_f32 v[32:33], v[36:37], 0 op_sel_hi:[1,0]
	s_mov_b32 s0, 0xa0000
	v_pk_add_f32 v[36:37], v[28:29], 0 op_sel_hi:[1,0]
	v_pk_add_f32 v[28:29], v[26:27], 0 op_sel_hi:[1,0]
	v_cvt_pk_bf16_f32 v26, v34, v35
	v_cvt_pk_bf16_f32 v27, v32, v33
	v_add_co_u32_e32 v32, vcc, s0, v130
	v_cvt_pk_bf16_f32 v28, v28, v29
	v_cvt_pk_bf16_f32 v29, v36, v37
	s_mov_b64 s[0:1], 0xb0000
	s_nop 0
	v_addc_co_u32_e32 v33, vcc, 0, v131, vcc
	global_store_dwordx4 v[32:33], v[26:29], off
	s_nop 1
	s_nop 1
	v_cvt_pk_bf16_f32 v17, v16, v17
	v_cvt_pk_bf16_f32 v16, v14, v15
	v_cvt_pk_bf16_f32 v14, v22, v23
	v_cvt_pk_bf16_f32 v15, v24, v25
	s_nop 0
	global_store_dwordx4 v[30:31], v[14:17], off offset:256
	s_nop 1
	s_nop 1
	v_lshl_add_u64 v[14:15], v[130:131], 0, s[0:1]
	v_pk_add_f32 v[16:17], v[20:21], 0 op_sel_hi:[1,0]
	s_mov_b32 s0, 0xb0000
	v_pk_add_f32 v[20:21], v[12:13], 0 op_sel_hi:[1,0]
	v_pk_add_f32 v[12:13], v[10:11], 0 op_sel_hi:[1,0]
	v_cvt_pk_bf16_f32 v10, v18, v19
	v_cvt_pk_bf16_f32 v11, v16, v17
	v_add_co_u32_e32 v16, vcc, s0, v130
	v_cvt_pk_bf16_f32 v12, v12, v13
	v_cvt_pk_bf16_f32 v13, v20, v21
	s_nop 1
	v_addc_co_u32_e32 v17, vcc, 0, v131, vcc
	global_store_dwordx4 v[16:17], v[10:13], off
	s_nop 1
	s_nop 1
	v_cvt_pk_bf16_f32 v5, v4, v5
	v_cvt_pk_bf16_f32 v4, v2, v3
	v_cvt_pk_bf16_f32 v2, v6, v7
	v_cvt_pk_bf16_f32 v3, v8, v9
	s_nop 0
	global_store_dwordx4 v[14:15], v[2:5], off offset:256
	s_nop 1
	s_waitcnt vmcnt(0)
	s_barrier
	s_nop 0
	v_mov_b32_e32 v3, v143

.LBB0_1101:
	v_lshl_add_u32 v152, s28, 8, v1
	v_lshl_or_b32 v144, s51, 8, v147
	v_readlane_b32 s2, v252, 2
	v_ashrrev_i32_e32 v145, 31, v144
	v_readlane_b32 s3, v252, 3
	v_ashrrev_i32_e32 v153, 31, v152
	v_lshl_add_u64 v[154:155], v[144:145], 1, s[2:3]
	v_lshlrev_b64 v[144:145], 11, v[152:153]
	v_lshl_add_u64 v[144:145], v[154:155], 0, v[144:145]
	v_cvt_pk_bf16_f32 v125, v124, v125
	v_cvt_pk_bf16_f32 v124, v122, v123
	v_cvt_pk_bf16_f32 v122, v126, v127
	v_cvt_pk_bf16_f32 v123, v128, v129
	global_store_dwordx4 v[144:145], v[122:125], off
	s_nop 1
	v_pk_add_f32 v[114:115], v[114:115], 0 op_sel_hi:[1,0]
	v_cvt_pk_bf16_f32 v113, v112, v113
	v_cvt_pk_bf16_f32 v112, v110, v111
	v_cvt_pk_bf16_f32 v110, v118, v119
	v_cvt_pk_bf16_f32 v111, v120, v121
	global_store_dwordx4 v[144:145], v[110:113], off offset:256
	s_nop 1
	v_pk_add_f32 v[98:99], v[98:99], 0 op_sel_hi:[1,0]
	v_or_b32_e32 v110, 16, v152
	v_ashrrev_i32_e32 v111, 31, v110
	v_lshlrev_b64 v[110:111], 11, v[110:111]
	v_lshl_add_u64 v[110:111], v[154:155], 0, v[110:111]
	v_pk_add_f32 v[112:113], v[116:117], 0 op_sel_hi:[1,0]
	v_pk_add_f32 v[116:117], v[108:109], 0 op_sel_hi:[1,0]
	v_pk_add_f32 v[108:109], v[106:107], 0 op_sel_hi:[1,0]
	v_cvt_pk_bf16_f32 v106, v114, v115
	v_cvt_pk_bf16_f32 v107, v112, v113
	v_cvt_pk_bf16_f32 v108, v108, v109
	v_cvt_pk_bf16_f32 v109, v116, v117
	global_store_dwordx4 v[110:111], v[106:109], off
	s_nop 1
	v_pk_add_f32 v[82:83], v[82:83], 0 op_sel_hi:[1,0]
	v_cvt_pk_bf16_f32 v97, v96, v97
	v_cvt_pk_bf16_f32 v96, v94, v95
	v_cvt_pk_bf16_f32 v94, v102, v103
	v_cvt_pk_bf16_f32 v95, v104, v105
	global_store_dwordx4 v[110:111], v[94:97], off offset:256
	s_nop 1
	s_mov_b64 s[2:3], 0x40000
	v_or_b32_e32 v94, 32, v152
	v_ashrrev_i32_e32 v95, 31, v94
	v_lshlrev_b64 v[94:95], 11, v[94:95]
	v_lshl_add_u64 v[94:95], v[154:155], 0, v[94:95]
	v_pk_add_f32 v[96:97], v[100:101], 0 op_sel_hi:[1,0]
	v_pk_add_f32 v[100:101], v[92:93], 0 op_sel_hi:[1,0]
	v_pk_add_f32 v[92:93], v[90:91], 0 op_sel_hi:[1,0]
	v_cvt_pk_bf16_f32 v90, v98, v99
	v_cvt_pk_bf16_f32 v91, v96, v97
	v_cvt_pk_bf16_f32 v92, v92, v93
	v_cvt_pk_bf16_f32 v93, v100, v101
	global_store_dwordx4 v[94:95], v[90:93], off
	s_nop 1
	v_cvt_pk_bf16_f32 v81, v80, v81
	v_cvt_pk_bf16_f32 v80, v78, v79
	v_cvt_pk_bf16_f32 v78, v86, v87
	v_cvt_pk_bf16_f32 v79, v88, v89
	global_store_dwordx4 v[94:95], v[78:81], off offset:256
	s_nop 1
	v_pk_add_f32 v[50:51], v[50:51], 0 op_sel_hi:[1,0]
	v_or_b32_e32 v78, 48, v152
	v_ashrrev_i32_e32 v79, 31, v78
	v_lshlrev_b64 v[78:79], 11, v[78:79]
	v_lshl_add_u64 v[78:79], v[154:155], 0, v[78:79]
	v_pk_add_f32 v[80:81], v[84:85], 0 op_sel_hi:[1,0]
	v_pk_add_f32 v[84:85], v[76:77], 0 op_sel_hi:[1,0]
	v_pk_add_f32 v[76:77], v[74:75], 0 op_sel_hi:[1,0]
	v_cvt_pk_bf16_f32 v74, v82, v83
	v_cvt_pk_bf16_f32 v75, v80, v81
	v_cvt_pk_bf16_f32 v76, v76, v77
	v_cvt_pk_bf16_f32 v77, v84, v85
	global_store_dwordx4 v[78:79], v[74:77], off
	s_nop 1
	v_pk_add_f32 v[34:35], v[34:35], 0 op_sel_hi:[1,0]
	v_cvt_pk_bf16_f32 v69, v68, v69
	v_cvt_pk_bf16_f32 v68, v66, v67
	v_cvt_pk_bf16_f32 v66, v70, v71
	v_cvt_pk_bf16_f32 v67, v72, v73
	global_store_dwordx4 v[78:79], v[66:69], off offset:256
	s_nop 1
	v_pk_add_f32 v[18:19], v[18:19], 0 op_sel_hi:[1,0]
	v_lshl_add_u64 v[66:67], v[144:145], 0, s[2:3]
	s_mov_b32 s2, 0x40000
	v_cvt_pk_bf16_f32 v61, v60, v61
	v_cvt_pk_bf16_f32 v60, v58, v59
	v_cvt_pk_bf16_f32 v58, v62, v63
	v_add_co_u32_e32 v62, vcc, s2, v144
	v_cvt_pk_bf16_f32 v59, v64, v65
	s_mov_b64 s[2:3], 0x48000
	s_nop 0
	v_addc_co_u32_e32 v63, vcc, 0, v145, vcc
	global_store_dwordx4 v[62:63], v[58:61], off
	s_nop 1
	s_nop 0
	v_cvt_pk_bf16_f32 v49, v48, v49
	v_cvt_pk_bf16_f32 v48, v46, v47
	v_cvt_pk_bf16_f32 v46, v54, v55
	v_cvt_pk_bf16_f32 v47, v56, v57
	s_nop 0
	global_store_dwordx4 v[66:67], v[46:49], off offset:256
	s_nop 1
	s_nop 1
	v_lshl_add_u64 v[46:47], v[144:145], 0, s[2:3]
	v_pk_add_f32 v[48:49], v[52:53], 0 op_sel_hi:[1,0]
	s_mov_b32 s2, 0x48000
	v_pk_add_f32 v[52:53], v[44:45], 0 op_sel_hi:[1,0]
	v_pk_add_f32 v[44:45], v[42:43], 0 op_sel_hi:[1,0]
	v_cvt_pk_bf16_f32 v42, v50, v51
	v_cvt_pk_bf16_f32 v43, v48, v49
	v_add_co_u32_e32 v48, vcc, s2, v144
	v_cvt_pk_bf16_f32 v44, v44, v45
	v_cvt_pk_bf16_f32 v45, v52, v53
	s_mov_b64 s[2:3], -1
	s_nop 0
	v_addc_co_u32_e32 v49, vcc, 0, v145, vcc
	global_store_dwordx4 v[48:49], v[42:45], off
	s_nop 1
	s_nop 1
	v_cvt_pk_bf16_f32 v33, v32, v33
	v_cvt_pk_bf16_f32 v32, v30, v31
	v_cvt_pk_bf16_f32 v30, v38, v39
	v_cvt_pk_bf16_f32 v31, v40, v41
	s_nop 0
	global_store_dwordx4 v[46:47], v[30:33], off offset:256
	s_nop 1
	s_nop 1
	v_pk_add_f32 v[32:33], v[36:37], 0 op_sel_hi:[1,0]
	v_pk_add_f32 v[36:37], v[28:29], 0 op_sel_hi:[1,0]
	v_pk_add_f32 v[28:29], v[26:27], 0 op_sel_hi:[1,0]
	v_cvt_pk_bf16_f32 v26, v34, v35
	v_cvt_pk_bf16_f32 v27, v32, v33
	v_add_co_u32_e32 v32, vcc, s49, v144
	v_cvt_pk_bf16_f32 v28, v28, v29
	v_cvt_pk_bf16_f32 v29, v36, v37
	v_lshl_add_u64 v[30:31], v[144:145], 0, s[10:11]
	s_nop 0
	v_addc_co_u32_e32 v33, vcc, 0, v145, vcc
	global_store_dwordx4 v[32:33], v[26:29], off
	s_nop 1
	s_nop 1
	v_cvt_pk_bf16_f32 v17, v16, v17
	v_cvt_pk_bf16_f32 v16, v14, v15
	v_cvt_pk_bf16_f32 v14, v22, v23
	v_cvt_pk_bf16_f32 v15, v24, v25
	s_nop 0
	global_store_dwordx4 v[30:31], v[14:17], off offset:256
	s_nop 1
	s_nop 1
	v_pk_add_f32 v[16:17], v[20:21], 0 op_sel_hi:[1,0]
	v_pk_add_f32 v[20:21], v[12:13], 0 op_sel_hi:[1,0]
	v_pk_add_f32 v[12:13], v[10:11], 0 op_sel_hi:[1,0]
	v_cvt_pk_bf16_f32 v10, v18, v19
	v_cvt_pk_bf16_f32 v11, v16, v17
	v_add_co_u32_e32 v16, vcc, s50, v144
	v_lshl_add_u64 v[14:15], v[144:145], 0, s[12:13]
	s_nop 0
	v_addc_co_u32_e32 v17, vcc, 0, v145, vcc
	v_cvt_pk_bf16_f32 v12, v12, v13
	v_cvt_pk_bf16_f32 v13, v20, v21
	global_store_dwordx4 v[16:17], v[10:13], off
	s_nop 1
	s_andn2_b64 vcc, exec, s[22:23]
	s_nop 0
	v_cvt_pk_bf16_f32 v5, v4, v5
	v_cvt_pk_bf16_f32 v4, v2, v3
	v_cvt_pk_bf16_f32 v2, v6, v7
	v_cvt_pk_bf16_f32 v3, v8, v9
	s_nop 0
	global_store_dwordx4 v[14:15], v[2:5], off offset:256
	s_nop 1
	s_cbranch_vccnz .LBB0_1089
	s_andn2_b64 vcc, exec, s[4:5]
	s_cbranch_vccnz .LBB0_1088
	s_barrier
	s_branch .LBB0_1088

.LBB0_1139:
	s_mov_b32 s3, 0x800000
	s_and_b64 s[0:1], s[0:1], exec
	s_cselect_b32 s0, s3, 0xa00000
	v_readlane_b32 s4, v253, 63
	v_lshl_or_b32 v1, s8, 8, v1
	v_readlane_b32 s5, v252, 0
	s_add_u32 s0, s4, s0
	v_or_b32_e32 v1, s2, v1
	v_mov_b32_e32 v131, 0
	s_addc_u32 s1, s5, 0
	v_lshl_add_u32 v132, s10, 8, v130
	v_lshlrev_b32_e32 v130, 1, v1
	v_mov_b32_e32 v133, v131
	v_lshl_add_u64 v[134:135], s[0:1], 0, v[130:131]
	v_lshlrev_b64 v[136:137], 11, v[132:133]
	v_lshl_add_u64 v[136:137], v[134:135], 0, v[136:137]
	v_cvt_pk_bf16_f32 v125, v124, v125
	v_cvt_pk_bf16_f32 v124, v122, v123
	v_cvt_pk_bf16_f32 v122, v126, v127
	v_cvt_pk_bf16_f32 v123, v128, v129
	global_store_dwordx4 v[136:137], v[122:125], off
	s_nop 1
	v_or_b32_e32 v130, 16, v132
	v_cvt_pk_bf16_f32 v117, v116, v117
	v_cvt_pk_bf16_f32 v116, v114, v115
	v_cvt_pk_bf16_f32 v114, v118, v119
	v_cvt_pk_bf16_f32 v115, v120, v121
	global_store_dwordx4 v[136:137], v[114:117], off offset:256
	s_nop 1
	v_lshlrev_b64 v[114:115], 11, v[130:131]
	v_lshl_add_u64 v[114:115], v[134:135], 0, v[114:115]
	v_cvt_pk_bf16_f32 v109, v108, v109
	v_cvt_pk_bf16_f32 v108, v106, v107
	v_cvt_pk_bf16_f32 v106, v110, v111
	v_cvt_pk_bf16_f32 v107, v112, v113
	global_store_dwordx4 v[114:115], v[106:109], off
	s_nop 1
	v_or_b32_e32 v130, 32, v132
	v_cvt_pk_bf16_f32 v101, v100, v101
	v_cvt_pk_bf16_f32 v100, v98, v99
	v_cvt_pk_bf16_f32 v98, v102, v103
	v_cvt_pk_bf16_f32 v99, v104, v105
	global_store_dwordx4 v[114:115], v[98:101], off offset:256
	s_nop 1
	v_lshlrev_b64 v[98:99], 11, v[130:131]
	v_lshl_add_u64 v[98:99], v[134:135], 0, v[98:99]
	v_cvt_pk_bf16_f32 v93, v92, v93
	v_cvt_pk_bf16_f32 v92, v90, v91
	v_cvt_pk_bf16_f32 v90, v94, v95
	v_cvt_pk_bf16_f32 v91, v96, v97
	v_or_b32_e32 v130, 48, v132
	global_store_dwordx4 v[98:99], v[90:93], off
	s_nop 1
	v_cvt_pk_bf16_f32 v85, v84, v85
	v_cvt_pk_bf16_f32 v84, v82, v83
	v_cvt_pk_bf16_f32 v82, v86, v87
	v_cvt_pk_bf16_f32 v83, v88, v89
	global_store_dwordx4 v[98:99], v[82:85], off offset:256
	s_nop 1
	v_pk_add_f32 v[64:65], v[64:65], 0 op_sel_hi:[1,0]
	v_lshlrev_b64 v[82:83], 11, v[130:131]
	v_lshl_add_u64 v[82:83], v[134:135], 0, v[82:83]
	v_cvt_pk_bf16_f32 v77, v76, v77
	v_cvt_pk_bf16_f32 v76, v74, v75
	v_cvt_pk_bf16_f32 v74, v78, v79
	v_cvt_pk_bf16_f32 v75, v80, v81
	v_add_u32_e32 v130, 0x80, v132
	global_store_dwordx4 v[82:83], v[74:77], off
	s_nop 1
	v_pk_add_f32 v[62:63], v[62:63], 0 op_sel_hi:[1,0]
	v_cvt_pk_bf16_f32 v61, v60, v61
	v_cvt_pk_bf16_f32 v60, v58, v59
	v_cvt_pk_bf16_f32 v58, v66, v67
	v_cvt_pk_bf16_f32 v59, v68, v69
	global_store_dwordx4 v[82:83], v[58:61], off offset:256
	s_nop 1
	v_lshlrev_b64 v[58:59], 11, v[130:131]
	v_lshl_add_u64 v[66:67], v[134:135], 0, v[58:59]
	v_pk_add_f32 v[58:59], v[70:71], 0 op_sel_hi:[1,0]
	v_pk_add_f32 v[60:61], v[72:73], 0 op_sel_hi:[1,0]
	v_cvt_pk_bf16_f32 v58, v58, v59
	v_add_u32_e32 v130, 0x90, v132
	v_cvt_pk_bf16_f32 v59, v60, v61
	v_cvt_pk_bf16_f32 v60, v62, v63
	v_cvt_pk_bf16_f32 v61, v64, v65
	global_store_dwordx4 v[66:67], v[58:61], off
	s_nop 1
	v_cvt_pk_bf16_f32 v53, v52, v53
	v_cvt_pk_bf16_f32 v52, v50, v51
	v_cvt_pk_bf16_f32 v50, v54, v55
	v_cvt_pk_bf16_f32 v51, v56, v57
	global_store_dwordx4 v[66:67], v[50:53], off offset:256
	s_nop 1
	v_lshlrev_b64 v[50:51], 11, v[130:131]
	v_lshl_add_u64 v[50:51], v[134:135], 0, v[50:51]
	v_cvt_pk_bf16_f32 v45, v44, v45
	v_cvt_pk_bf16_f32 v44, v42, v43
	v_cvt_pk_bf16_f32 v42, v46, v47
	v_cvt_pk_bf16_f32 v43, v48, v49
	v_add_u32_e32 v130, 0xa0, v132
	global_store_dwordx4 v[50:51], v[42:45], off
	s_nop 1
	v_cvt_pk_bf16_f32 v37, v36, v37
	v_cvt_pk_bf16_f32 v36, v34, v35
	v_cvt_pk_bf16_f32 v34, v38, v39
	v_cvt_pk_bf16_f32 v35, v40, v41
	global_store_dwordx4 v[50:51], v[34:37], off offset:256
	s_nop 1
	v_lshlrev_b64 v[34:35], 11, v[130:131]
	v_lshl_add_u64 v[34:35], v[134:135], 0, v[34:35]
	v_cvt_pk_bf16_f32 v29, v28, v29
	v_cvt_pk_bf16_f32 v28, v26, v27
	v_cvt_pk_bf16_f32 v26, v30, v31
	v_cvt_pk_bf16_f32 v27, v32, v33
	v_add_u32_e32 v130, 0xb0, v132
	global_store_dwordx4 v[34:35], v[26:29], off
	s_nop 1
	s_mov_b32 s28, s33
	s_nop 0
	v_cvt_pk_bf16_f32 v21, v20, v21
	v_cvt_pk_bf16_f32 v20, v18, v19
	v_cvt_pk_bf16_f32 v18, v22, v23
	v_cvt_pk_bf16_f32 v19, v24, v25
	s_nop 0
	global_store_dwordx4 v[34:35], v[18:21], off offset:256
	s_nop 1
	s_nop 1
	v_lshlrev_b64 v[18:19], 11, v[130:131]
	v_lshl_add_u64 v[18:19], v[134:135], 0, v[18:19]
	v_cvt_pk_bf16_f32 v13, v12, v13
	v_cvt_pk_bf16_f32 v12, v10, v11
	v_cvt_pk_bf16_f32 v10, v14, v15
	v_cvt_pk_bf16_f32 v11, v16, v17
	s_nop 0
	global_store_dwordx4 v[18:19], v[10:13], off
	s_nop 1
	s_nop 1
	v_cvt_pk_bf16_f32 v5, v4, v5
	v_cvt_pk_bf16_f32 v4, v2, v3
	v_cvt_pk_bf16_f32 v2, v6, v7
	v_cvt_pk_bf16_f32 v3, v8, v9
	s_nop 0
	global_store_dwordx4 v[18:19], v[2:5], off offset:256
	s_nop 1
	s_waitcnt vmcnt(0)
	s_barrier

.LBB0_1242:
	v_lshl_add_u32 v152, s34, 8, v1
	v_lshl_or_b32 v144, s57, 8, v147
	v_readlane_b32 s2, v252, 2
	v_ashrrev_i32_e32 v145, 31, v144
	v_readlane_b32 s3, v252, 3
	v_ashrrev_i32_e32 v153, 31, v152
	v_lshl_add_u64 v[154:155], v[144:145], 1, s[2:3]
	v_lshlrev_b64 v[144:145], 11, v[152:153]
	v_lshl_add_u64 v[144:145], v[154:155], 0, v[144:145]
	v_cvt_pk_bf16_f32 v125, v124, v125
	v_cvt_pk_bf16_f32 v124, v122, v123
	v_cvt_pk_bf16_f32 v122, v126, v127
	v_cvt_pk_bf16_f32 v123, v128, v129
	global_store_dwordx4 v[144:145], v[122:125], off
	s_nop 1
	v_pk_add_f32 v[114:115], v[114:115], 0 op_sel_hi:[1,0]
	v_cvt_pk_bf16_f32 v113, v112, v113
	v_cvt_pk_bf16_f32 v112, v110, v111
	v_cvt_pk_bf16_f32 v110, v118, v119
	v_cvt_pk_bf16_f32 v111, v120, v121
	global_store_dwordx4 v[144:145], v[110:113], off offset:256
	s_nop 1
	v_pk_add_f32 v[98:99], v[98:99], 0 op_sel_hi:[1,0]
	v_or_b32_e32 v110, 16, v152
	v_ashrrev_i32_e32 v111, 31, v110
	v_lshlrev_b64 v[110:111], 11, v[110:111]
	v_lshl_add_u64 v[110:111], v[154:155], 0, v[110:111]
	v_pk_add_f32 v[112:113], v[116:117], 0 op_sel_hi:[1,0]
	v_pk_add_f32 v[116:117], v[108:109], 0 op_sel_hi:[1,0]
	v_pk_add_f32 v[108:109], v[106:107], 0 op_sel_hi:[1,0]
	v_cvt_pk_bf16_f32 v106, v114, v115
	v_cvt_pk_bf16_f32 v107, v112, v113
	v_cvt_pk_bf16_f32 v108, v108, v109
	v_cvt_pk_bf16_f32 v109, v116, v117
	global_store_dwordx4 v[110:111], v[106:109], off
	s_nop 1
	v_pk_add_f32 v[82:83], v[82:83], 0 op_sel_hi:[1,0]
	v_cvt_pk_bf16_f32 v97, v96, v97
	v_cvt_pk_bf16_f32 v96, v94, v95
	v_cvt_pk_bf16_f32 v94, v102, v103
	v_cvt_pk_bf16_f32 v95, v104, v105
	global_store_dwordx4 v[110:111], v[94:97], off offset:256
	s_nop 1
	v_or_b32_e32 v94, 32, v152
	v_ashrrev_i32_e32 v95, 31, v94
	v_lshlrev_b64 v[94:95], 11, v[94:95]
	v_lshl_add_u64 v[94:95], v[154:155], 0, v[94:95]
	v_pk_add_f32 v[96:97], v[100:101], 0 op_sel_hi:[1,0]
	v_pk_add_f32 v[100:101], v[92:93], 0 op_sel_hi:[1,0]
	v_pk_add_f32 v[92:93], v[90:91], 0 op_sel_hi:[1,0]
	v_cvt_pk_bf16_f32 v90, v98, v99
	v_cvt_pk_bf16_f32 v91, v96, v97
	v_cvt_pk_bf16_f32 v92, v92, v93
	v_cvt_pk_bf16_f32 v93, v100, v101
	global_store_dwordx4 v[94:95], v[90:93], off
	s_nop 1
	s_mov_b64 s[2:3], 0x40000
	v_cvt_pk_bf16_f32 v81, v80, v81
	v_cvt_pk_bf16_f32 v80, v78, v79
	v_cvt_pk_bf16_f32 v78, v86, v87
	v_cvt_pk_bf16_f32 v79, v88, v89
	global_store_dwordx4 v[94:95], v[78:81], off offset:256
	s_nop 1
	v_pk_add_f32 v[50:51], v[50:51], 0 op_sel_hi:[1,0]
	v_or_b32_e32 v78, 48, v152
	v_ashrrev_i32_e32 v79, 31, v78
	v_lshlrev_b64 v[78:79], 11, v[78:79]
	v_lshl_add_u64 v[78:79], v[154:155], 0, v[78:79]
	v_pk_add_f32 v[80:81], v[84:85], 0 op_sel_hi:[1,0]
	v_pk_add_f32 v[84:85], v[76:77], 0 op_sel_hi:[1,0]
	v_pk_add_f32 v[76:77], v[74:75], 0 op_sel_hi:[1,0]
	v_cvt_pk_bf16_f32 v74, v82, v83
	v_cvt_pk_bf16_f32 v75, v80, v81
	v_cvt_pk_bf16_f32 v76, v76, v77
	v_cvt_pk_bf16_f32 v77, v84, v85
	global_store_dwordx4 v[78:79], v[74:77], off
	s_nop 1
	v_pk_add_f32 v[34:35], v[34:35], 0 op_sel_hi:[1,0]
	v_cvt_pk_bf16_f32 v69, v68, v69
	v_cvt_pk_bf16_f32 v68, v66, v67
	v_cvt_pk_bf16_f32 v66, v70, v71
	v_cvt_pk_bf16_f32 v67, v72, v73
	global_store_dwordx4 v[78:79], v[66:69], off offset:256
	s_nop 1
	v_pk_add_f32 v[18:19], v[18:19], 0 op_sel_hi:[1,0]
	v_cvt_pk_bf16_f32 v61, v60, v61
	v_cvt_pk_bf16_f32 v60, v58, v59
	v_cvt_pk_bf16_f32 v58, v62, v63
	v_add_co_u32_e32 v62, vcc, s53, v144
	v_cvt_pk_bf16_f32 v59, v64, v65
	v_lshl_add_u64 v[66:67], v[144:145], 0, s[2:3]
	s_nop 0
	v_addc_co_u32_e32 v63, vcc, 0, v145, vcc
	global_store_dwordx4 v[62:63], v[58:61], off
	s_nop 1
	s_mov_b64 s[2:3], -1
	v_cvt_pk_bf16_f32 v49, v48, v49
	v_cvt_pk_bf16_f32 v48, v46, v47
	v_cvt_pk_bf16_f32 v46, v54, v55
	v_cvt_pk_bf16_f32 v47, v56, v57
	s_nop 0
	global_store_dwordx4 v[66:67], v[46:49], off offset:256
	s_nop 1
	s_nop 1
	v_pk_add_f32 v[48:49], v[52:53], 0 op_sel_hi:[1,0]
	v_pk_add_f32 v[52:53], v[44:45], 0 op_sel_hi:[1,0]
	v_pk_add_f32 v[44:45], v[42:43], 0 op_sel_hi:[1,0]
	v_cvt_pk_bf16_f32 v42, v50, v51
	v_cvt_pk_bf16_f32 v43, v48, v49
	v_add_co_u32_e32 v48, vcc, s54, v144
	v_cvt_pk_bf16_f32 v44, v44, v45
	v_cvt_pk_bf16_f32 v45, v52, v53
	v_lshl_add_u64 v[46:47], v[144:145], 0, s[12:13]
	s_nop 0
	v_addc_co_u32_e32 v49, vcc, 0, v145, vcc
	global_store_dwordx4 v[48:49], v[42:45], off
	s_nop 1
	s_nop 1
	v_cvt_pk_bf16_f32 v33, v32, v33
	v_cvt_pk_bf16_f32 v32, v30, v31
	v_cvt_pk_bf16_f32 v30, v38, v39
	v_cvt_pk_bf16_f32 v31, v40, v41
	s_nop 0
	global_store_dwordx4 v[46:47], v[30:33], off offset:256
	s_nop 1
	s_nop 1
	v_pk_add_f32 v[32:33], v[36:37], 0 op_sel_hi:[1,0]
	v_pk_add_f32 v[36:37], v[28:29], 0 op_sel_hi:[1,0]
	v_pk_add_f32 v[28:29], v[26:27], 0 op_sel_hi:[1,0]
	v_cvt_pk_bf16_f32 v26, v34, v35
	v_cvt_pk_bf16_f32 v27, v32, v33
	v_add_co_u32_e32 v32, vcc, s55, v144
	v_cvt_pk_bf16_f32 v28, v28, v29
	v_cvt_pk_bf16_f32 v29, v36, v37
	v_lshl_add_u64 v[30:31], v[144:145], 0, s[14:15]
	s_nop 0
	v_addc_co_u32_e32 v33, vcc, 0, v145, vcc
	global_store_dwordx4 v[32:33], v[26:29], off
	s_nop 1
	s_nop 1
	v_cvt_pk_bf16_f32 v17, v16, v17
	v_cvt_pk_bf16_f32 v16, v14, v15
	v_cvt_pk_bf16_f32 v14, v22, v23
	v_cvt_pk_bf16_f32 v15, v24, v25
	s_nop 0
	global_store_dwordx4 v[30:31], v[14:17], off offset:256
	s_nop 1
	s_nop 1
	v_pk_add_f32 v[16:17], v[20:21], 0 op_sel_hi:[1,0]
	v_pk_add_f32 v[20:21], v[12:13], 0 op_sel_hi:[1,0]
	v_pk_add_f32 v[12:13], v[10:11], 0 op_sel_hi:[1,0]
	v_cvt_pk_bf16_f32 v10, v18, v19
	v_cvt_pk_bf16_f32 v11, v16, v17
	v_add_co_u32_e32 v16, vcc, s56, v144
	v_lshl_add_u64 v[14:15], v[144:145], 0, s[16:17]
	s_nop 0
	v_addc_co_u32_e32 v17, vcc, 0, v145, vcc
	v_cvt_pk_bf16_f32 v12, v12, v13
	v_cvt_pk_bf16_f32 v13, v20, v21
	global_store_dwordx4 v[16:17], v[10:13], off
	s_nop 1
	s_andn2_b64 vcc, exec, s[26:27]
	s_nop 0
	v_cvt_pk_bf16_f32 v5, v4, v5
	v_cvt_pk_bf16_f32 v4, v2, v3
	v_cvt_pk_bf16_f32 v2, v6, v7
	v_cvt_pk_bf16_f32 v3, v8, v9
	s_nop 0
	global_store_dwordx4 v[14:15], v[2:5], off offset:256
	s_nop 1
	s_cbranch_vccnz .LBB0_1230
	s_andn2_b64 vcc, exec, s[6:7]
	s_cbranch_vccnz .LBB0_1229
	s_barrier
	s_branch .LBB0_1229

.LBB0_1389:
	v_lshl_add_u32 v142, s17, 8, v131
	v_lshl_or_b32 v131, s18, 8, v157
	v_or_b32_e32 v140, s23, v131
	v_readlane_b32 s0, v252, 2
	v_ashrrev_i32_e32 v141, 31, v140
	v_readlane_b32 s1, v252, 3
	v_ashrrev_i32_e32 v143, 31, v142
	v_lshl_add_u64 v[144:145], v[140:141], 1, s[0:1]
	v_lshlrev_b64 v[140:141], 11, v[142:143]
	v_lshl_add_u64 v[140:141], v[144:145], 0, v[140:141]
	v_cvt_pk_bf16_f32 v125, v124, v125
	v_cvt_pk_bf16_f32 v124, v122, v123
	v_cvt_pk_bf16_f32 v122, v126, v127
	v_cvt_pk_bf16_f32 v123, v128, v129
	global_store_dwordx4 v[140:141], v[122:125], off
	s_nop 1
	v_pk_add_f32 v[114:115], v[114:115], 0 op_sel_hi:[1,0]
	v_cvt_pk_bf16_f32 v113, v112, v113
	v_cvt_pk_bf16_f32 v112, v110, v111
	v_cvt_pk_bf16_f32 v110, v118, v119
	v_cvt_pk_bf16_f32 v111, v120, v121
	global_store_dwordx4 v[140:141], v[110:113], off offset:256
	s_nop 1
	v_pk_add_f32 v[98:99], v[98:99], 0 op_sel_hi:[1,0]
	v_or_b32_e32 v110, 16, v142
	v_ashrrev_i32_e32 v111, 31, v110
	v_lshlrev_b64 v[110:111], 11, v[110:111]
	v_lshl_add_u64 v[110:111], v[144:145], 0, v[110:111]
	v_pk_add_f32 v[112:113], v[116:117], 0 op_sel_hi:[1,0]
	v_pk_add_f32 v[116:117], v[108:109], 0 op_sel_hi:[1,0]
	v_pk_add_f32 v[108:109], v[106:107], 0 op_sel_hi:[1,0]
	v_cvt_pk_bf16_f32 v106, v114, v115
	v_cvt_pk_bf16_f32 v107, v112, v113
	v_cvt_pk_bf16_f32 v108, v108, v109
	v_cvt_pk_bf16_f32 v109, v116, v117
	global_store_dwordx4 v[110:111], v[106:109], off
	s_nop 1
	v_pk_add_f32 v[82:83], v[82:83], 0 op_sel_hi:[1,0]
	v_cvt_pk_bf16_f32 v97, v96, v97
	v_cvt_pk_bf16_f32 v96, v94, v95
	v_cvt_pk_bf16_f32 v94, v102, v103
	v_cvt_pk_bf16_f32 v95, v104, v105
	global_store_dwordx4 v[110:111], v[94:97], off offset:256
	s_nop 1
	s_mov_b64 s[0:1], 0x40000
	v_or_b32_e32 v94, 32, v142
	v_ashrrev_i32_e32 v95, 31, v94
	v_lshlrev_b64 v[94:95], 11, v[94:95]
	v_lshl_add_u64 v[94:95], v[144:145], 0, v[94:95]
	v_pk_add_f32 v[96:97], v[100:101], 0 op_sel_hi:[1,0]
	v_pk_add_f32 v[100:101], v[92:93], 0 op_sel_hi:[1,0]
	v_pk_add_f32 v[92:93], v[90:91], 0 op_sel_hi:[1,0]
	v_cvt_pk_bf16_f32 v90, v98, v99
	v_cvt_pk_bf16_f32 v91, v96, v97
	v_cvt_pk_bf16_f32 v92, v92, v93
	v_cvt_pk_bf16_f32 v93, v100, v101
	global_store_dwordx4 v[94:95], v[90:93], off
	s_nop 1
	v_cvt_pk_bf16_f32 v81, v80, v81
	v_cvt_pk_bf16_f32 v80, v78, v79
	v_cvt_pk_bf16_f32 v78, v86, v87
	v_cvt_pk_bf16_f32 v79, v88, v89
	global_store_dwordx4 v[94:95], v[78:81], off offset:256
	s_nop 1
	v_pk_add_f32 v[50:51], v[50:51], 0 op_sel_hi:[1,0]
	v_or_b32_e32 v78, 48, v142
	v_ashrrev_i32_e32 v79, 31, v78
	v_lshlrev_b64 v[78:79], 11, v[78:79]
	v_lshl_add_u64 v[78:79], v[144:145], 0, v[78:79]
	v_pk_add_f32 v[80:81], v[84:85], 0 op_sel_hi:[1,0]
	v_pk_add_f32 v[84:85], v[76:77], 0 op_sel_hi:[1,0]
	v_pk_add_f32 v[76:77], v[74:75], 0 op_sel_hi:[1,0]
	v_cvt_pk_bf16_f32 v74, v82, v83
	v_cvt_pk_bf16_f32 v75, v80, v81
	v_cvt_pk_bf16_f32 v76, v76, v77
	v_cvt_pk_bf16_f32 v77, v84, v85
	global_store_dwordx4 v[78:79], v[74:77], off
	s_nop 1
	v_pk_add_f32 v[34:35], v[34:35], 0 op_sel_hi:[1,0]
	v_cvt_pk_bf16_f32 v69, v68, v69
	v_cvt_pk_bf16_f32 v68, v66, v67
	v_cvt_pk_bf16_f32 v66, v70, v71
	v_cvt_pk_bf16_f32 v67, v72, v73
	global_store_dwordx4 v[78:79], v[66:69], off offset:256
	s_nop 1
	v_pk_add_f32 v[18:19], v[18:19], 0 op_sel_hi:[1,0]
	v_lshl_add_u64 v[66:67], v[140:141], 0, s[0:1]
	s_mov_b32 s0, 0x40000
	v_cvt_pk_bf16_f32 v61, v60, v61
	v_cvt_pk_bf16_f32 v60, v58, v59
	v_cvt_pk_bf16_f32 v58, v62, v63
	v_add_co_u32_e32 v62, vcc, s0, v140
	v_cvt_pk_bf16_f32 v59, v64, v65
	s_mov_b64 s[0:1], 0x48000
	s_nop 0
	v_addc_co_u32_e32 v63, vcc, 0, v141, vcc
	global_store_dwordx4 v[62:63], v[58:61], off
	s_nop 1
	s_mov_b32 s28, s33
	v_cvt_pk_bf16_f32 v49, v48, v49
	v_cvt_pk_bf16_f32 v48, v46, v47
	v_cvt_pk_bf16_f32 v46, v54, v55
	v_cvt_pk_bf16_f32 v47, v56, v57
	s_nop 0
	global_store_dwordx4 v[66:67], v[46:49], off offset:256
	s_nop 1
	s_nop 1
	v_lshl_add_u64 v[46:47], v[140:141], 0, s[0:1]
	v_pk_add_f32 v[48:49], v[52:53], 0 op_sel_hi:[1,0]
	s_mov_b32 s0, 0x48000
	v_pk_add_f32 v[52:53], v[44:45], 0 op_sel_hi:[1,0]
	v_pk_add_f32 v[44:45], v[42:43], 0 op_sel_hi:[1,0]
	v_cvt_pk_bf16_f32 v42, v50, v51
	v_cvt_pk_bf16_f32 v43, v48, v49
	v_add_co_u32_e32 v48, vcc, s0, v140
	v_cvt_pk_bf16_f32 v44, v44, v45
	v_cvt_pk_bf16_f32 v45, v52, v53
	s_mov_b64 s[0:1], 0x50000
	s_nop 0
	v_addc_co_u32_e32 v49, vcc, 0, v141, vcc
	global_store_dwordx4 v[48:49], v[42:45], off
	s_nop 1
	s_nop 1
	v_cvt_pk_bf16_f32 v33, v32, v33
	v_cvt_pk_bf16_f32 v32, v30, v31
	v_cvt_pk_bf16_f32 v30, v38, v39
	v_cvt_pk_bf16_f32 v31, v40, v41
	s_nop 0
	global_store_dwordx4 v[46:47], v[30:33], off offset:256
	s_nop 1
	s_nop 1
	v_lshl_add_u64 v[30:31], v[140:141], 0, s[0:1]
	v_pk_add_f32 v[32:33], v[36:37], 0 op_sel_hi:[1,0]
	s_mov_b32 s0, 0x50000
	v_pk_add_f32 v[36:37], v[28:29], 0 op_sel_hi:[1,0]
	v_pk_add_f32 v[28:29], v[26:27], 0 op_sel_hi:[1,0]
	v_cvt_pk_bf16_f32 v26, v34, v35
	v_cvt_pk_bf16_f32 v27, v32, v33
	v_add_co_u32_e32 v32, vcc, s0, v140
	v_cvt_pk_bf16_f32 v28, v28, v29
	v_cvt_pk_bf16_f32 v29, v36, v37
	s_mov_b64 s[0:1], 0x58000
	s_nop 0
	v_addc_co_u32_e32 v33, vcc, 0, v141, vcc
	global_store_dwordx4 v[32:33], v[26:29], off
	s_nop 1
	s_nop 1
	v_cvt_pk_bf16_f32 v17, v16, v17
	v_cvt_pk_bf16_f32 v16, v14, v15
	v_cvt_pk_bf16_f32 v14, v22, v23
	v_cvt_pk_bf16_f32 v15, v24, v25
	s_nop 0
	global_store_dwordx4 v[30:31], v[14:17], off offset:256
	s_nop 1
	s_nop 1
	v_lshl_add_u64 v[14:15], v[140:141], 0, s[0:1]
	v_pk_add_f32 v[16:17], v[20:21], 0 op_sel_hi:[1,0]
	s_mov_b32 s0, 0x58000
	v_pk_add_f32 v[20:21], v[12:13], 0 op_sel_hi:[1,0]
	v_pk_add_f32 v[12:13], v[10:11], 0 op_sel_hi:[1,0]
	v_cvt_pk_bf16_f32 v10, v18, v19
	v_cvt_pk_bf16_f32 v11, v16, v17
	v_add_co_u32_e32 v16, vcc, s0, v140
	v_cvt_pk_bf16_f32 v12, v12, v13
	v_cvt_pk_bf16_f32 v13, v20, v21
	s_nop 1
	v_addc_co_u32_e32 v17, vcc, 0, v141, vcc
	global_store_dwordx4 v[16:17], v[10:13], off
	s_nop 1
	s_nop 1
	v_cvt_pk_bf16_f32 v5, v4, v5
	v_cvt_pk_bf16_f32 v4, v2, v3
	v_cvt_pk_bf16_f32 v2, v6, v7
	v_cvt_pk_bf16_f32 v3, v8, v9
	s_nop 0
	global_store_dwordx4 v[14:15], v[2:5], off offset:256
	s_nop 1
	s_waitcnt vmcnt(0)
	s_barrier

.LBB0_1447:
	v_lshl_add_u32 v152, s55, 8, v1
	v_lshl_or_b32 v144, s54, 8, v147
	v_readlane_b32 s2, v252, 2
	v_ashrrev_i32_e32 v145, 31, v144
	v_readlane_b32 s3, v252, 3
	v_ashrrev_i32_e32 v153, 31, v152
	v_lshl_add_u64 v[154:155], v[144:145], 1, s[2:3]
	v_lshlrev_b64 v[144:145], 11, v[152:153]
	v_lshl_add_u64 v[144:145], v[154:155], 0, v[144:145]
	v_cvt_pk_bf16_f32 v125, v124, v125
	v_cvt_pk_bf16_f32 v124, v122, v123
	v_cvt_pk_bf16_f32 v122, v126, v127
	v_cvt_pk_bf16_f32 v123, v128, v129
	global_store_dwordx4 v[144:145], v[122:125], off
	s_nop 1
	v_pk_add_f32 v[114:115], v[114:115], 0 op_sel_hi:[1,0]
	v_cvt_pk_bf16_f32 v113, v112, v113
	v_cvt_pk_bf16_f32 v112, v110, v111
	v_cvt_pk_bf16_f32 v110, v118, v119
	v_cvt_pk_bf16_f32 v111, v120, v121
	global_store_dwordx4 v[144:145], v[110:113], off offset:256
	s_nop 1
	v_pk_add_f32 v[98:99], v[98:99], 0 op_sel_hi:[1,0]
	v_or_b32_e32 v110, 16, v152
	v_ashrrev_i32_e32 v111, 31, v110
	v_lshlrev_b64 v[110:111], 11, v[110:111]
	v_lshl_add_u64 v[110:111], v[154:155], 0, v[110:111]
	v_pk_add_f32 v[112:113], v[116:117], 0 op_sel_hi:[1,0]
	v_pk_add_f32 v[116:117], v[108:109], 0 op_sel_hi:[1,0]
	v_pk_add_f32 v[108:109], v[106:107], 0 op_sel_hi:[1,0]
	v_cvt_pk_bf16_f32 v106, v114, v115
	v_cvt_pk_bf16_f32 v107, v112, v113
	v_cvt_pk_bf16_f32 v108, v108, v109
	v_cvt_pk_bf16_f32 v109, v116, v117
	global_store_dwordx4 v[110:111], v[106:109], off
	s_nop 1
	v_pk_add_f32 v[82:83], v[82:83], 0 op_sel_hi:[1,0]
	v_cvt_pk_bf16_f32 v97, v96, v97
	v_cvt_pk_bf16_f32 v96, v94, v95
	v_cvt_pk_bf16_f32 v94, v102, v103
	v_cvt_pk_bf16_f32 v95, v104, v105
	global_store_dwordx4 v[110:111], v[94:97], off offset:256
	s_nop 1
	v_or_b32_e32 v94, 32, v152
	v_ashrrev_i32_e32 v95, 31, v94
	v_lshlrev_b64 v[94:95], 11, v[94:95]
	v_lshl_add_u64 v[94:95], v[154:155], 0, v[94:95]
	v_pk_add_f32 v[96:97], v[100:101], 0 op_sel_hi:[1,0]
	v_pk_add_f32 v[100:101], v[92:93], 0 op_sel_hi:[1,0]
	v_pk_add_f32 v[92:93], v[90:91], 0 op_sel_hi:[1,0]
	v_cvt_pk_bf16_f32 v90, v98, v99
	v_cvt_pk_bf16_f32 v91, v96, v97
	v_cvt_pk_bf16_f32 v92, v92, v93
	v_cvt_pk_bf16_f32 v93, v100, v101
	global_store_dwordx4 v[94:95], v[90:93], off
	s_nop 1
	v_cvt_pk_bf16_f32 v81, v80, v81
	v_cvt_pk_bf16_f32 v80, v78, v79
	v_cvt_pk_bf16_f32 v78, v86, v87
	v_cvt_pk_bf16_f32 v79, v88, v89
	v_pk_add_f32 v[50:51], v[50:51], 0 op_sel_hi:[1,0]
	global_store_dwordx4 v[94:95], v[78:81], off offset:256
	s_nop 1
	v_or_b32_e32 v78, 48, v152
	v_ashrrev_i32_e32 v79, 31, v78
	v_lshlrev_b64 v[78:79], 11, v[78:79]
	v_lshl_add_u64 v[78:79], v[154:155], 0, v[78:79]
	v_pk_add_f32 v[80:81], v[84:85], 0 op_sel_hi:[1,0]
	v_pk_add_f32 v[84:85], v[76:77], 0 op_sel_hi:[1,0]
	v_pk_add_f32 v[76:77], v[74:75], 0 op_sel_hi:[1,0]
	v_cvt_pk_bf16_f32 v74, v82, v83
	v_cvt_pk_bf16_f32 v75, v80, v81
	v_pk_add_f32 v[34:35], v[34:35], 0 op_sel_hi:[1,0]
	v_cvt_pk_bf16_f32 v76, v76, v77
	v_cvt_pk_bf16_f32 v77, v84, v85
	global_store_dwordx4 v[78:79], v[74:77], off
	s_nop 1
	v_cvt_pk_bf16_f32 v69, v68, v69
	v_cvt_pk_bf16_f32 v68, v66, v67
	v_cvt_pk_bf16_f32 v66, v70, v71
	v_cvt_pk_bf16_f32 v67, v72, v73
	v_pk_add_f32 v[18:19], v[18:19], 0 op_sel_hi:[1,0]
	global_store_dwordx4 v[78:79], v[66:69], off offset:256
	s_nop 1
	s_mov_b64 s[2:3], -1
	v_cvt_pk_bf16_f32 v61, v60, v61
	v_cvt_pk_bf16_f32 v60, v58, v59
	v_cvt_pk_bf16_f32 v58, v62, v63
	v_add_co_u32_e32 v62, vcc, s48, v144
	v_cvt_pk_bf16_f32 v59, v64, v65
	v_lshl_add_u64 v[66:67], v[144:145], 0, s[8:9]
	s_nop 0
	v_addc_co_u32_e32 v63, vcc, 0, v145, vcc
	global_store_dwordx4 v[62:63], v[58:61], off
	s_nop 1
	s_nop 0
	v_cvt_pk_bf16_f32 v49, v48, v49
	v_cvt_pk_bf16_f32 v48, v46, v47
	v_cvt_pk_bf16_f32 v46, v54, v55
	v_cvt_pk_bf16_f32 v47, v56, v57
	s_nop 0
	global_store_dwordx4 v[66:67], v[46:49], off offset:256
	s_nop 1
	s_nop 1
	v_pk_add_f32 v[48:49], v[52:53], 0 op_sel_hi:[1,0]
	v_pk_add_f32 v[52:53], v[44:45], 0 op_sel_hi:[1,0]
	v_pk_add_f32 v[44:45], v[42:43], 0 op_sel_hi:[1,0]
	v_cvt_pk_bf16_f32 v42, v50, v51
	v_cvt_pk_bf16_f32 v43, v48, v49
	v_add_co_u32_e32 v48, vcc, s49, v144
	v_cvt_pk_bf16_f32 v44, v44, v45
	v_cvt_pk_bf16_f32 v45, v52, v53
	v_lshl_add_u64 v[46:47], v[144:145], 0, s[10:11]
	s_nop 0
	v_addc_co_u32_e32 v49, vcc, 0, v145, vcc
	global_store_dwordx4 v[48:49], v[42:45], off
	s_nop 1
	s_nop 1
	v_cvt_pk_bf16_f32 v33, v32, v33
	v_cvt_pk_bf16_f32 v32, v30, v31
	v_cvt_pk_bf16_f32 v30, v38, v39
	v_cvt_pk_bf16_f32 v31, v40, v41
	s_nop 0
	global_store_dwordx4 v[46:47], v[30:33], off offset:256
	s_nop 1
	s_nop 1
	v_pk_add_f32 v[32:33], v[36:37], 0 op_sel_hi:[1,0]
	v_pk_add_f32 v[36:37], v[28:29], 0 op_sel_hi:[1,0]
	v_pk_add_f32 v[28:29], v[26:27], 0 op_sel_hi:[1,0]
	v_cvt_pk_bf16_f32 v26, v34, v35
	v_cvt_pk_bf16_f32 v27, v32, v33
	v_add_co_u32_e32 v32, vcc, s50, v144
	v_cvt_pk_bf16_f32 v28, v28, v29
	v_cvt_pk_bf16_f32 v29, v36, v37
	v_lshl_add_u64 v[30:31], v[144:145], 0, s[12:13]
	s_nop 0
	v_addc_co_u32_e32 v33, vcc, 0, v145, vcc
	global_store_dwordx4 v[32:33], v[26:29], off
	s_nop 1
	s_nop 1
	v_cvt_pk_bf16_f32 v17, v16, v17
	v_cvt_pk_bf16_f32 v16, v14, v15
	v_cvt_pk_bf16_f32 v14, v22, v23
	v_cvt_pk_bf16_f32 v15, v24, v25
	s_nop 0
	global_store_dwordx4 v[30:31], v[14:17], off offset:256
	s_nop 1
	s_nop 1
	v_pk_add_f32 v[16:17], v[20:21], 0 op_sel_hi:[1,0]
	v_pk_add_f32 v[20:21], v[12:13], 0 op_sel_hi:[1,0]
	v_pk_add_f32 v[12:13], v[10:11], 0 op_sel_hi:[1,0]
	v_cvt_pk_bf16_f32 v10, v18, v19
	v_cvt_pk_bf16_f32 v11, v16, v17
	v_add_co_u32_e32 v16, vcc, s51, v144
	v_lshl_add_u64 v[14:15], v[144:145], 0, s[14:15]
	s_nop 0
	v_addc_co_u32_e32 v17, vcc, 0, v145, vcc
	v_cvt_pk_bf16_f32 v12, v12, v13
	v_cvt_pk_bf16_f32 v13, v20, v21
	global_store_dwordx4 v[16:17], v[10:13], off
	s_nop 1
	s_andn2_b64 vcc, exec, s[20:21]
	s_nop 0
	v_cvt_pk_bf16_f32 v5, v4, v5
	v_cvt_pk_bf16_f32 v4, v2, v3
	v_cvt_pk_bf16_f32 v2, v6, v7
	v_cvt_pk_bf16_f32 v3, v8, v9
	s_nop 0
	global_store_dwordx4 v[14:15], v[2:5], off offset:256
	s_nop 1
	s_cbranch_vccnz .LBB0_1435
	s_andn2_b64 vcc, exec, s[4:5]
	s_cbranch_vccnz .LBB0_1434
	s_barrier
	s_branch .LBB0_1434
